# k27 + in-proj tile assignment rebalanced: rounds 3-5 take the tile of workgroup c^64/c^128/c^192 (same per-XCD tile sets), spreading the heavy epilogue columns across workgroups
# speedup vs baseline: 1.0159x; 1.0159x over previous
.LBB0_475:
	s_add_i32 s56, s56, 1
	s_mul_i32 s1, s56, s86
	s_mul_hi_u32 s2, s56, s78
	s_add_i32 s1, s2, s1
	s_mul_i32 s2, s56, s78
	v_readlane_b32 s3, v254, 40
	s_mov_b32 s10, 0
	s_cmp_eq_u32 s56, 3
	s_cselect_b32 s10, 64, s10
	s_cmp_eq_u32 s56, 4
	s_cselect_b32 s10, 128, s10
	s_cmp_eq_u32 s56, 5
	s_cselect_b32 s10, 192, s10
	s_cmp_eq_u32 s78, 0x100
	s_cselect_b32 s10, s10, 0
	s_xor_b32 s3, s3, s10
	s_add_u32 s2, s2, s3
	s_addc_u32 s3, s1, s47
	v_mov_b64_e32 v[2:3], 0x600
	v_cmp_gt_i64_e32 vcc, s[2:3], v[248:249]
	v_cmp_lt_i64_e64 s[6:7], s[2:3], v[2:3]
	s_cbranch_vccnz .LBB0_477
	s_ashr_i32 s1, s2, 31
	s_lshr_b32 s1, s1, 29
	s_add_i32 s1, s2, s1
	s_ashr_i32 s3, s1, 3
	s_and_b32 s1, s1, -8
	s_sub_i32 s1, s2, s1
	s_cmp_lt_i32 s1, 0
	s_movk_i32 s2, 0xc1
	s_cselect_b32 s2, s2, 0xc0
	s_mul_i32 s1, s1, s2
	s_add_i32 s1, s1, s3
	s_mul_hi_i32 s2, s1, 0x2aaaaaab
	s_lshr_b32 s3, s2, 31
	s_ashr_i32 s2, s2, 4
	s_add_i32 s2, s2, s3
	s_lshl_b32 s3, s2, 3
	s_sub_i32 s10, 0x80, s3
	s_min_i32 s10, s10, 8
	s_abs_i32 s11, s10
	s_waitcnt lgkmcnt(0)
	v_cvt_f32_u32_e32 v0, s11
	s_sub_i32 s13, 0, s11
	s_mulk_i32 s2, 0x60
	s_sub_i32 s1, s1, s2
	v_rcp_iflag_f32_e32 v0, v0
	s_abs_i32 s2, s1
	s_xor_b32 s12, s1, s10
	s_ashr_i32 s12, s12, 31
	v_mul_f32_e32 v0, 0x4f7ffffe, v0
	v_cvt_u32_f32_e32 v0, v0
	s_nop 0
	v_readfirstlane_b32 s14, v0
	s_mul_i32 s13, s13, s14
	s_mul_hi_u32 s13, s14, s13
	s_add_i32 s14, s14, s13
	s_mul_hi_u32 s13, s2, s14
	s_mul_i32 s14, s13, s11
	s_sub_i32 s2, s2, s14
	s_add_i32 s15, s13, 1
	s_sub_i32 s14, s2, s11
	s_cmp_ge_u32 s2, s11
	s_cselect_b32 s13, s15, s13
	s_cselect_b32 s2, s14, s2
	s_add_i32 s14, s13, 1
	s_cmp_ge_u32 s2, s11
	s_cselect_b32 s2, s14, s13
	s_xor_b32 s2, s2, s12
	s_sub_i32 s26, s2, s12
	s_mul_i32 s2, s26, s10
	s_sub_i32 s1, s1, s2
	s_add_i32 s28, s3, s1
